# phase 0 work lists re-based: transposes on waves 0..1791 (stride 1792), LoRA-2 blocks on waves 896..1791, adaLN GEMV items on waves 1792..2047
# speedup vs baseline: 1.0103x; 1.0103x over previous
.LBB0_6:
	s_or_b64 exec, exec, s[4:5]
	s_load_dwordx2 s[4:5], s[0:1], 0x128
	s_load_dwordx8 s[8:15], s[0:1], 0x88
	s_load_dwordx4 s[20:23], s[0:1], 0x70
	v_writelane_b32 v251, s0, 13
	s_load_dwordx4 s[16:19], s[0:1], 0x8
	v_mov_b32_e32 v31, v214
	s_lshl_b32 s85, s2, 3
	v_writelane_b32 v251, s1, 14
	s_movk_i32 s0, 0x4100
	v_ashrrev_i32_e32 v50, 6, v31
	v_and_b32_e32 v6, 63, v31
	v_add_u32_e32 v76, s85, v50
	v_mul_lo_u32 v1, v50, s0
	s_movk_i32 s0, 0x700
	s_waitcnt lgkmcnt(0)
	s_lshl_b32 s42, s4, 3
	v_add_u32_e32 v9, 0, v1
	v_readfirstlane_b32 s24, v2
	v_readfirstlane_b32 s25, v3
	v_cmp_gt_i32_e32 vcc, s0, v76
	v_lshlrev_b32_e32 v13, 3, v6
	v_lshrrev_b32_e32 v8, 5, v6
	v_and_b32_e32 v30, 31, v31
	s_and_saveexec_b64 s[4:5], vcc
	v_writelane_b32 v251, s85, 15
	s_cbranch_execz .LBB0_29
	v_and_b32_e32 v18, 56, v13
	v_mov_b32_e32 v3, 0
	v_lshlrev_b32_e32 v2, 1, v18
	v_lshl_add_u64 v[16:17], s[24:25], 0, v[2:3]
	s_mov_b64 s[0:1], 0x3600000
	s_mov_b64 s[26:27], 0x2000000
	v_lshl_add_u64 v[4:5], v[16:17], 0, s[0:1]
	s_mov_b64 s[0:1], 0x2800000
	v_lshl_add_u64 v[14:15], v[16:17], 0, s[26:27]
	s_mov_b64 s[26:27], 0x1800000
	v_lshl_add_u64 v[10:11], v[16:17], 0, s[0:1]
	v_lshl_add_u64 v[16:17], v[16:17], 0, s[26:27]
	v_readlane_b32 s26, v251, 13
	v_readlane_b32 s27, v251, 14
	s_load_dwordx2 s[26:27], s[26:27], 0x60
	v_lshrrev_b32_e32 v33, 3, v6
	v_mul_u32_u24_e32 v1, 0x104, v18
	v_lshlrev_b32_e32 v2, 2, v33
	v_lshl_add_u32 v32, v6, 2, v9
	v_add3_u32 v34, v9, v1, v2
	v_mul_u32_u24_e32 v1, 0x84, v18
	v_or_b32_e32 v35, 8, v33
	v_or_b32_e32 v36, 16, v33
	v_or_b32_e32 v37, 24, v33
	v_or_b32_e32 v38, 32, v33
	v_or_b32_e32 v39, 40, v33
	v_or_b32_e32 v40, 48, v33
	v_or_b32_e32 v41, 56, v33
	v_lshl_add_u32 v12, v30, 2, v9
	s_movk_i32 s0, 0x84
	v_add3_u32 v42, v9, v1, v2
	v_mov_b32_e32 v1, v8
	s_movk_i32 s1, 0x2000
	s_movk_i32 s3, 0x4000
	s_movk_i32 s33, 0x6000
	s_mov_b32 s40, 0x8000
	s_mov_b32 s41, 0xa000
	s_mov_b32 s43, 0xc000
	s_mov_b32 s44, 0xe000
	s_mov_b32 s45, 0x68000
	s_mov_b32 s46, 0x6a000
	s_mov_b32 s47, 0x6c000
	s_mov_b32 s48, 0x6e000
	s_mov_b32 s49, 0x70000
	s_mov_b32 s50, 0x72000
	s_mov_b32 s51, 0x74000
	s_mov_b32 s52, 0x76000
	s_mov_b32 s53, 0x78000
	s_mov_b32 s54, 0x7a000
	s_mov_b32 s55, 0x7c000
	s_mov_b32 s56, 0x7e000
	s_movk_i32 s57, 0x7fff
	s_mov_b32 s58, 0xffff0000
	s_movk_i32 s59, 0x400
	s_movk_i32 s60, 0x1000
	v_lshlrev_b32_e32 v18, 1, v18
	v_mov_b32_e32 v43, 0x1e580
	v_lshlrev_b32_e32 v20, 2, v6
	v_add_u32_e32 v44, 0x400, v32
	v_add_u32_e32 v45, 0x800, v32
	v_add_u32_e32 v46, 0xc00, v32
	v_add_u32_e32 v47, 0x1000, v32
	v_add_u32_e32 v48, 0x1400, v32
	v_add_u32_e32 v49, 0x1800, v32
	v_add_u32_e32 v51, 0x1c00, v32
	v_add_u32_e32 v52, 0x2000, v32
	v_add_u32_e32 v53, 0x2400, v32
	v_add_u32_e32 v54, 0x2800, v32
	v_add_u32_e32 v55, 0x2c00, v32
	v_add_u32_e32 v56, 0x3000, v32
	v_add_u32_e32 v57, 0x3400, v32
	v_add_u32_e32 v58, 0x3800, v32
	v_add_u32_e32 v59, 0x3c00, v32
	v_add_u32_e32 v60, 0x400, v34
	v_mov_b32_e32 v61, 0x400
	v_mov_b32_e32 v62, 0x58
	v_mov_b32_e32 v63, 0x50
	v_mov_b32_e32 v64, 0x48
	v_mov_b32_e32 v65, 6
	v_mov_b32_e32 v66, v76
	s_movk_i32 s61, 0x3000
	s_movk_i32 s62, 0x5000
	s_movk_i32 s63, 0x7000
	s_mov_b32 s64, 0x9000
	s_mov_b32 s65, 0xb000
	s_mov_b32 s66, 0xd000
	s_mov_b32 s67, 0xf000
	s_movk_i32 s68, 0xab
	s_movk_i32 s69, 0x60
	s_movk_i32 s70, 0x7fe
	s_movk_i32 s71, 0x113f
	s_mov_b64 s[28:29], 0
	s_branch .LBB0_9
.LBB0_8:
	s_or_b64 exec, exec, s[30:31]
	v_add_u32_e32 v66, 0x700, v66
	v_cmp_lt_i32_e32 vcc, s71, v66
	s_or_b64 s[28:29], vcc, s[28:29]
	s_andn2_b64 exec, exec, s[28:29]
	s_cbranch_execz .LBB0_29

.LBB0_37:
	s_or_b64 exec, exec, s[4:5]
	v_add_u32_e32 v52, 0xc80, v76
	v_and_b32_e32 v52, 0xfff, v52
	s_movk_i32 s0, 0x380
	v_cmp_gt_i32_e32 vcc, s0, v52
	s_and_saveexec_b64 s[4:5], vcc
	s_cbranch_execz .LBB0_48
	v_and_b32_e32 v38, 24, v13
	v_mul_u32_u24_e32 v1, 0x84, v38
	v_and_b32_e32 v4, 60, v6
	v_add3_u32 v1, v9, v1, v4
	v_lshlrev_b32_e32 v4, 7, v6
	v_lshl_or_b32 v2, v8, 11, v30
	v_and_b32_e32 v40, 0x1e00, v4
	v_readlane_b32 s0, v251, 0
	s_add_u32 s8, s24, 0x3000000
	v_lshl_add_u32 v5, v30, 2, v9
	v_mul_u32_u24_e32 v11, 0x84, v8
	v_or_b32_e32 v8, 0x1000, v2
	v_or_b32_e32 v10, 0x2000, v2
	v_or_b32_e32 v12, 0x3000, v2
	v_or_b32_e32 v14, 0x4000, v2
	v_or_b32_e32 v16, 0x5000, v2
	v_or_b32_e32 v18, 0x6000, v2
	v_or_b32_e32 v20, 0x7000, v2
	v_or_b32_e32 v22, 0x8000, v2
	v_or_b32_e32 v24, 0x9000, v2
	v_or_b32_e32 v26, 0xa000, v2
	v_or_b32_e32 v28, 0xb000, v2
	v_or_b32_e32 v30, 0xc000, v2
	v_or_b32_e32 v32, 0xd000, v2
	v_or_b32_e32 v34, 0xe000, v2
	v_or_b32_e32 v36, 0xf000, v2
	v_or_b32_e32 v42, 0x2000, v40
	v_lshlrev_b32_e32 v4, 5, v50
	v_readlane_b32 s1, v251, 1
	s_addc_u32 s9, s25, 0
	v_mov_b32_e32 v3, 0
	v_lshlrev_b32_e32 v7, 5, v52
	s_lshl_b32 s0, s0, 8
	s_mov_b64 s[12:13], 0
	v_lshlrev_b32_e32 v4, 2, v2
	v_add_u32_e32 v51, v5, v11
	v_lshlrev_b32_e32 v8, 2, v8
	v_lshlrev_b32_e32 v10, 2, v10
	v_lshlrev_b32_e32 v12, 2, v12
	v_lshlrev_b32_e32 v14, 2, v14
	v_lshlrev_b32_e32 v16, 2, v16
	v_lshlrev_b32_e32 v18, 2, v18
	v_lshlrev_b32_e32 v20, 2, v20
	v_lshlrev_b32_e32 v22, 2, v22
	v_lshlrev_b32_e32 v24, 2, v24
	v_lshlrev_b32_e32 v26, 2, v26
	v_lshlrev_b32_e32 v28, 2, v28
	v_lshlrev_b32_e32 v30, 2, v30
	v_lshlrev_b32_e32 v32, 2, v32
	v_lshlrev_b32_e32 v34, 2, v34
	v_lshlrev_b32_e32 v36, 2, v36
	v_lshlrev_b32_e32 v38, 1, v38
	s_movk_i32 s1, 0x7fff
	s_mov_b32 s3, 0xffff0000
	v_lshlrev_b32_e32 v40, 1, v40
	v_lshlrev_b32_e32 v42, 1, v42
	s_movk_i32 s28, 0x37f
	s_nop 0
	s_branch .LBB0_40

.LBB0_48:
	s_or_b64 exec, exec, s[4:5]
	v_add_u32_e32 v76, 0x100, v76
	v_and_b32_e32 v76, 0x7ff, v76
	s_movk_i32 s0, 0x100
	v_cmp_gt_i32_e32 vcc, s0, v76
	s_and_saveexec_b64 s[4:5], vcc
	s_cbranch_execz .LBB0_55
	v_lshlrev_b32_e32 v2, 8, v50
	v_readlane_b32 s0, v251, 0
	s_add_u32 s8, s24, 0xde80000
	v_lshlrev_b32_e32 v1, 2, v6
	v_lshlrev_b32_e32 v2, 8, v76
	v_readlane_b32 s1, v251, 1
	s_addc_u32 s9, s25, 0
	v_or_b32_e32 v77, v2, v1
	s_lshl_b32 s0, s0, 11
	s_mov_b64 s[10:11], 0
	s_mov_b32 s1, 0xc000
	s_mov_b32 s3, 0x18000
	s_waitcnt lgkmcnt(0)
	s_mov_b32 s26, 0x24000
	s_mov_b32 s27, 0x30000
	s_mov_b32 s28, 0x3c000
	s_mov_b32 s29, 0x48000
	s_mov_b32 s30, 0x54000
	s_mov_b32 s31, 0x60000
	s_mov_b32 s33, 0x6c000
	s_mov_b32 s34, 0x78000
	s_mov_b32 s35, 0x84000
	s_mov_b32 s36, 0x90000
	s_mov_b32 s37, 0x9c000
	s_mov_b32 s38, 0xa8000
	s_mov_b32 s39, 0xb4000
	s_mov_b64 s[12:13], 0x2000
	s_movk_i32 s40, 0x2000
	s_mov_b64 s[14:15], 0x4000
	s_movk_i32 s41, 0x4000
	s_mov_b64 s[20:21], 0x6000
	s_movk_i32 s43, 0x6000
	s_mov_b64 s[22:23], 0xc0000
	s_movk_i32 s44, 0xff
	s_branch .LBB0_51
